# nt hint also on the read-once residual loads of the GEMM4 epilogue
# baseline (speedup 1.0000x reference)
;     __device__ __forceinline__ void operator()(const f32x4 (&acc)[2][2][4][2], const Unit& u, int wr, int wc, int fr, int fq) const {
;     ...
;         const bf16_t* H1B = (const bf16_t*)(ws + WS_XB); float* yp = out + O_YP;
; #pragma unroll
;         for (int ai = 0; ai < 2; ++ai) { u32x2 hw[4][2][2];
; #pragma unroll
;             for (int m = 0; m < 4; ++m)
; #pragma unroll
;                 for (int bj = 0; bj < 2; ++bj)
; #pragma unroll
;                     for (int n = 0; n < 2; ++n) hw[m][bj][n] = *(const u32x2*)(H1B + (size_t)(row0 + ai * HALF + m * 16) * 4096 + col0 + bj * HALF + n * 16);
; #pragma unroll
;             for (int m = 0; m < 4; ++m) { const int row = row0 + ai * HALF + m * 16;
;                 float* dst = (row >= 272 && row < G_MV) ? yp + (size_t)(row - 272) * 4096 : nullptr;
;                 if (dst) {
; #pragma unroll
;                     for (int bj = 0; bj < 2; ++bj)
; #pragma unroll
;                         for (int n = 0; n < 2; ++n) { const int c = col0 + bj * HALF + n * 16; const u32x2 w = hw[m][bj][n]; f32x4 h;
;                             h[0] = __builtin_bit_cast(float, w.x << 16); h[1] = __builtin_bit_cast(float, w.x & 0xffff0000u); h[2] = __builtin_bit_cast(float, w.y << 16); h[3] = __builtin_bit_cast(float, w.y & 0xffff0000u);
;                             *(f32x4*)(dst + c) = h + acc[ai][bj][m][n]; } } } }
.LBB0_3526:
	v_lshl_add_u32 v146, s4, 8, v136
	v_or_b32_e32 v150, 16, v146
	v_ashrrev_i32_e32 v145, 31, v144
	v_ashrrev_i32_e32 v151, 31, v150
	v_lshl_add_u64 v[148:149], v[144:145], 1, s[10:11]
	v_lshlrev_b64 v[150:151], 13, v[150:151]
	v_lshl_add_u64 v[150:151], v[148:149], 0, v[150:151]
	global_load_dwordx2 v[174:175], v[150:151], off nt
	global_load_dwordx2 v[172:173], v[150:151], off offset:32 nt
	global_load_dwordx2 v[170:171], v[150:151], off offset:256 nt
	global_load_dwordx2 v[168:169], v[150:151], off offset:288 nt
	v_or_b32_e32 v150, 32, v146
	v_ashrrev_i32_e32 v151, 31, v150
	v_lshlrev_b64 v[150:151], 13, v[150:151]
	v_lshl_add_u64 v[150:151], v[148:149], 0, v[150:151]
	global_load_dwordx2 v[166:167], v[150:151], off nt
	global_load_dwordx2 v[164:165], v[150:151], off offset:32 nt
	global_load_dwordx2 v[162:163], v[150:151], off offset:256 nt
	global_load_dwordx2 v[160:161], v[150:151], off offset:288 nt
	v_or_b32_e32 v150, 48, v146
	v_ashrrev_i32_e32 v151, 31, v150
	v_lshlrev_b64 v[150:151], 13, v[150:151]
	v_lshl_add_u64 v[150:151], v[148:149], 0, v[150:151]
	global_load_dwordx2 v[158:159], v[150:151], off nt
	global_load_dwordx2 v[156:157], v[150:151], off offset:32 nt
	global_load_dwordx2 v[154:155], v[150:151], off offset:256 nt
	global_load_dwordx2 v[152:153], v[150:151], off offset:288 nt
	v_add_u32_e32 v134, 0xfffffef0, v146
	v_cmp_gt_u32_e32 vcc, s55, v134
	s_and_b64 s[4:5], vcc, s[22:23]
	v_lshlrev_b32_e32 v150, 13, v146
	s_and_saveexec_b64 s[38:39], s[4:5]
	s_cbranch_execz .LBB0_3528
	v_mov_b32_e32 v151, v135
	v_lshl_add_u64 v[180:181], v[148:149], 0, v[150:151]
	global_load_dwordx2 v[182:183], v[180:181], off nt
	global_load_dwordx2 v[184:185], v[180:181], off offset:32 nt
	global_load_dwordx2 v[186:187], v[180:181], off offset:256 nt
	s_nop 0
	global_load_dwordx2 v[180:181], v[180:181], off offset:288 nt
	v_lshlrev_b32_e32 v134, 14, v134
	v_lshl_add_u64 v[188:189], s[8:9], 0, v[134:135]
	v_lshl_add_u64 v[188:189], v[144:145], 2, v[188:189]
	s_waitcnt vmcnt(0)
	v_lshlrev_b32_e32 v190, 16, v182
	v_and_b32_e32 v191, 0xffff0000, v182
	v_lshlrev_b32_e32 v182, 16, v183
	v_and_b32_e32 v183, 0xffff0000, v183
	v_lshlrev_b32_e32 v192, 16, v184
	v_and_b32_e32 v193, 0xffff0000, v184
	v_lshlrev_b32_e32 v184, 16, v185
	v_and_b32_e32 v185, 0xffff0000, v185
	v_lshlrev_b32_e32 v194, 16, v186
	v_and_b32_e32 v195, 0xffff0000, v186
	v_lshlrev_b32_e32 v186, 16, v187
	v_and_b32_e32 v187, 0xffff0000, v187
	v_lshlrev_b32_e32 v196, 16, v180
	v_and_b32_e32 v197, 0xffff0000, v180
	v_lshlrev_b32_e32 v180, 16, v181
	v_and_b32_e32 v181, 0xffff0000, v181
	v_pk_add_f32 v[128:129], v[128:129], v[182:183]
	v_pk_add_f32 v[126:127], v[126:127], v[190:191]
	v_pk_add_f32 v[124:125], v[124:125], v[184:185]
	v_pk_add_f32 v[122:123], v[122:123], v[192:193]
	v_pk_add_f32 v[120:121], v[120:121], v[186:187]
	v_pk_add_f32 v[118:119], v[118:119], v[194:195]
	v_pk_add_f32 v[116:117], v[116:117], v[180:181]
	v_pk_add_f32 v[114:115], v[114:115], v[196:197]
	global_store_dwordx4 v[188:189], v[126:129], off
	global_store_dwordx4 v[188:189], v[122:125], off offset:64
	global_store_dwordx4 v[188:189], v[118:121], off offset:512
	global_store_dwordx4 v[188:189], v[114:117], off offset:576

;     __device__ __forceinline__ void operator()(const f32x4 (&acc)[2][2][4][2], const Unit& u, int wr, int wc, int fr, int fq) const {
;     ...
;         for (int ai = 0; ai < 2; ++ai) { u32x2 hw[4][2][2];
; #pragma unroll
;             for (int m = 0; m < 4; ++m)
; #pragma unroll
;                 for (int bj = 0; bj < 2; ++bj)
; #pragma unroll
;                     for (int n = 0; n < 2; ++n) hw[m][bj][n] = *(const u32x2*)(H1B + (size_t)(row0 + ai * HALF + m * 16) * 4096 + col0 + bj * HALF + n * 16);
; #pragma unroll
;             for (int m = 0; m < 4; ++m) { const int row = row0 + ai * HALF + m * 16;
;                 float* dst = (row >= 272 && row < G_MV) ? yp + (size_t)(row - 272) * 4096 : nullptr;
;                 if (dst) {
; #pragma unroll
;                     for (int bj = 0; bj < 2; ++bj)
; #pragma unroll
;                         for (int n = 0; n < 2; ++n) { const int c = col0 + bj * HALF + n * 16; const u32x2 w = hw[m][bj][n]; f32x4 h;
;                             h[0] = __builtin_bit_cast(float, w.x << 16); h[1] = __builtin_bit_cast(float, w.x & 0xffff0000u); h[2] = __builtin_bit_cast(float, w.y << 16); h[3] = __builtin_bit_cast(float, w.y & 0xffff0000u);
;                             *(f32x4*)(dst + c) = h + acc[ai][bj][m][n]; } } } }
.LBB0_3534:
	s_or_b64 exec, exec, s[38:39]
	v_ashrrev_i32_e32 v147, 31, v146
	v_lshlrev_b64 v[66:67], 13, v[146:147]
	v_lshl_add_u64 v[66:67], v[148:149], 0, v[66:67]
	v_add_co_u32_e32 v70, vcc, 0x120000, v66
	v_lshl_add_u64 v[68:69], v[66:67], 0, s[24:25]
	s_nop 0
	v_addc_co_u32_e32 v71, vcc, 0, v67, vcc
	global_load_dwordx2 v[88:89], v[70:71], off nt
	global_load_dwordx2 v[86:87], v[68:69], off offset:32 nt
	global_load_dwordx2 v[84:85], v[68:69], off offset:256 nt
	global_load_dwordx2 v[82:83], v[68:69], off offset:288 nt
	v_add_co_u32_e32 v70, vcc, 0x140000, v66
	v_lshl_add_u64 v[68:69], v[66:67], 0, s[26:27]
	s_nop 0
	v_addc_co_u32_e32 v71, vcc, 0, v67, vcc
	v_lshl_add_u64 v[90:91], v[66:67], 0, s[28:29]
	v_add_co_u32_e32 v66, vcc, 0x160000, v66
	global_load_dwordx2 v[80:81], v[70:71], off nt
	global_load_dwordx2 v[78:79], v[68:69], off offset:32 nt
	global_load_dwordx2 v[76:77], v[68:69], off offset:256 nt
	global_load_dwordx2 v[74:75], v[68:69], off offset:288 nt
	v_addc_co_u32_e32 v67, vcc, 0, v67, vcc
	global_load_dwordx2 v[72:73], v[66:67], off nt
	global_load_dwordx2 v[70:71], v[90:91], off offset:32 nt
	global_load_dwordx2 v[68:69], v[90:91], off offset:256 nt
	s_nop 0
	global_load_dwordx2 v[66:67], v[90:91], off offset:288 nt
	v_add_u32_e32 v90, 0xffffff70, v146
	v_cmp_gt_u32_e32 vcc, s55, v90
	s_and_b64 s[4:5], vcc, s[22:23]
	s_and_saveexec_b64 s[38:39], s[4:5]
	s_cbranch_execz .LBB0_3536
	v_mov_b32_e32 v151, v135
	v_lshl_add_u64 v[92:93], v[148:149], 0, v[150:151]
	v_add_co_u32_e32 v92, vcc, 0x100000, v92
	v_lshlrev_b32_e32 v134, 14, v90
	s_nop 0
	v_addc_co_u32_e32 v93, vcc, 0, v93, vcc
	global_load_dwordx2 v[94:95], v[92:93], off nt
	global_load_dwordx2 v[96:97], v[92:93], off offset:32 nt
	global_load_dwordx2 v[98:99], v[92:93], off offset:256 nt
	s_nop 0
	global_load_dwordx2 v[92:93], v[92:93], off offset:288 nt
	v_lshl_add_u64 v[90:91], s[8:9], 0, v[134:135]
	v_lshl_add_u64 v[90:91], v[144:145], 2, v[90:91]
	s_waitcnt vmcnt(0)
	v_lshlrev_b32_e32 v100, 16, v94
	v_and_b32_e32 v101, 0xffff0000, v94
	v_lshlrev_b32_e32 v94, 16, v95
	v_and_b32_e32 v95, 0xffff0000, v95
	v_lshlrev_b32_e32 v102, 16, v96
	v_and_b32_e32 v103, 0xffff0000, v96
	v_lshlrev_b32_e32 v96, 16, v97
	v_and_b32_e32 v97, 0xffff0000, v97
	v_lshlrev_b32_e32 v104, 16, v98
	v_and_b32_e32 v105, 0xffff0000, v98
	v_lshlrev_b32_e32 v98, 16, v99
	v_and_b32_e32 v99, 0xffff0000, v99
	v_lshlrev_b32_e32 v106, 16, v92
	v_and_b32_e32 v107, 0xffff0000, v92
	v_lshlrev_b32_e32 v92, 16, v93
	v_and_b32_e32 v93, 0xffff0000, v93
	v_pk_add_f32 v[64:65], v[64:65], v[94:95]
	v_pk_add_f32 v[62:63], v[62:63], v[100:101]
	v_pk_add_f32 v[60:61], v[60:61], v[96:97]
	v_pk_add_f32 v[58:59], v[58:59], v[102:103]
	v_pk_add_f32 v[56:57], v[56:57], v[98:99]
	v_pk_add_f32 v[54:55], v[54:55], v[104:105]
	v_pk_add_f32 v[52:53], v[52:53], v[92:93]
	v_pk_add_f32 v[50:51], v[50:51], v[106:107]
	global_store_dwordx4 v[90:91], v[62:65], off
	global_store_dwordx4 v[90:91], v[58:61], off offset:64
	global_store_dwordx4 v[90:91], v[54:57], off offset:512
	global_store_dwordx4 v[90:91], v[50:53], off offset:576
